# scan S1 roles 2/3: cq>=2 lanes process their two 8-channel halves in swapped order (second-half loads at address^16 via a separate pointer, constants/step-vector stores at +-32 B twin bases): ds_write
# speedup vs baseline: 1.0035x; 1.0035x over previous
; __device__ __forceinline__ void load_raw16(Raw16& r, const bf16_t* __restrict__ z, int row, int t, int T, int col) {
;   const bf16_t* pz = z + (unsigned)(row * ZLD + col);
;   r.c0 = *(const uint4*)pz; r.c1 = *(const uint4*)(pz + 8);
;   r.p0 = make_uint4(0, 0, 0, 0); r.p1 = r.p0; r.n0 = r.p0; r.n1 = r.p0;
;   if (t > 0) { r.p0 = *(const uint4*)(pz - ZLD); r.p1 = *(const uint4*)(pz - ZLD + 8); }
;   if (t < T - 1) { r.n0 = *(const uint4*)(pz + ZLD); r.n1 = *(const uint4*)(pz + ZLD + 8); }
; __device__ __forceinline__ void scan_phase(PREF p, char* smem, const int wid_u) {
;     ...
;       if (1 < nch) {
;         const int is2 = 32 + th * 16 + tl;
;         const int t2 = d ? T - 1 - is2 : is2;
;         const int row2 = r0seq + t2;
;         if (role >= 2) load_raw16(ra, z, row2, t2, T, colA);
;         if (role == 3) load_raw16(rb, z, row2, t2, T, colB);
;         if (role < 2) {
;           const int is3 = 32 + th * 16 + fr, t3 = d ? T - 1 - is3 : is3;
;           const bf16_t* ap = P_ALORA + (unsigned)((r0seq + t3) * 256 + alo);
;           ra.c0 = *(const uint4*)ap; ra.c1 = *(const uint4*)(ap + 32);
;         }
;       }
.Lbt_skip:
	s_cmp_lt_u32 s90, 4
	s_cbranch_scc1 .Lswz_skip
	v_mbcnt_lo_u32_b32 v255, -1, 0
	v_mbcnt_hi_u32_b32 v255, -1, v255
	v_and_b32_e32 v255, 2, v255
	v_lshlrev_b32_e32 v255, 4, v255
	v_lshrrev_b32_e32 v56, 2, v255
	v_add_u32_e32 v74, v74, v56
	v_add_u32_e32 v76, v76, v56
	v_add_u32_e32 v57, s47, v170
	v_add3_u32 v56, v113, s93, 32
	v_add_u32_e32 v57, 0xffffffdf, v57
	v_cndmask_b32_e64 v58, v57, v56, s[2:3]
	v_add_u32_e32 v59, s91, v58
	v_mad_u64_u32 v[0:1], s[82:83], v59, s88, v[74:75]
	v_mov_b32_e32 v1, v79
	v_lshl_add_u64 v[56:57], v[0:1], 1, s[50:51]
	v_lshl_add_u64 v[4:5], v[56:57], 0, s[76:77]
	v_lshl_add_u64 v[8:9], v[56:57], 0, s[76:77]
	v_lshl_add_u64 v[0:1], v[56:57], 0, s[78:79]
	v_lshl_add_u64 v[28:29], v[56:57], 0, s[78:79]
	v_xor_b32_e32 v8, 16, v8
	v_xor_b32_e32 v28, 16, v28
	v_xor_b32_e32 v250, 16, v56
	v_mov_b32_e32 v251, v57
	global_load_dwordx4 v[12:15], v[56:57], off
	global_load_dwordx4 v[16:19], v[250:251], off
	global_load_dwordx4 v[4:7], v[4:5], off
	s_nop 0
	global_load_dwordx4 v[8:11], v[8:9], off
	global_load_dwordx4 v[0:3], v[0:1], off
	s_nop 0
	global_load_dwordx4 v[28:31], v[28:29], off
	s_cmp_lt_u32 s90, 6
	s_cbranch_scc1 .Lswz_skip
	v_mad_u64_u32 v[20:21], s[82:83], v59, s88, v[76:77]
	v_mov_b32_e32 v21, v79
	v_lshl_add_u64 v[56:57], v[20:21], 1, s[50:51]
	v_lshl_add_u64 v[36:37], v[56:57], 0, s[76:77]
	v_lshl_add_u64 v[40:41], v[56:57], 0, s[76:77]
	v_lshl_add_u64 v[32:33], v[56:57], 0, s[78:79]
	v_lshl_add_u64 v[44:45], v[56:57], 0, s[78:79]
	v_xor_b32_e32 v40, 16, v40
	v_xor_b32_e32 v44, 16, v44
	v_xor_b32_e32 v252, 16, v56
	v_mov_b32_e32 v253, v57
	global_load_dwordx4 v[24:27], v[56:57], off
	global_load_dwordx4 v[20:23], v[252:253], off
	global_load_dwordx4 v[36:39], v[36:37], off
	s_nop 0
	global_load_dwordx4 v[40:43], v[40:41], off
	global_load_dwordx4 v[32:35], v[32:33], off
	s_nop 0
	global_load_dwordx4 v[44:47], v[44:45], off

; __device__ __forceinline__ float quad_sum(float x) { x += dpp_f<0xB1>(x); x += dpp_f<0x4E>(x); return x; }
; __device__ __forceinline__ void scan_phase(PREF p, char* smem, const int wid_u) {
;     ...
;           shift16(ra, cst + 2 * 64 + cq * 16, cst + 0 * 64 + cq * 16, v16);
;           float kk[16], ss = 0.f;
; #pragma unroll
;           for (int q = 0; q < 16; ++q) { kk[q] = v16[q] * cst[5 * 64 + cq * 16 + q]; ss += kk[q] * kk[q]; }
;           ss = quad_sum(ss);
;           const float inv = 1.f / fmaxf(sqrtf(ss), 1e-12f);
; #pragma unroll
;           for (int q = 0; q < 4; ++q) {
;             *(f32x4*)(stepbuf + 1 * SV + j * 64 + cq * 16 + q * 4) = (f32x4){v16[q * 4], v16[q * 4 + 1], v16[q * 4 + 2], v16[q * 4 + 3]};
;             *(f32x4*)(stepbuf + 3 * SV + j * 64 + cq * 16 + q * 4) = (f32x4){-kk[q * 4] * inv, -kk[q * 4 + 1] * inv, -kk[q * 4 + 2] * inv, -kk[q * 4 + 3] * inv};
;           }
.LBB0_566:
	s_add_i32 s40, s94, -1
	s_cmp_lt_u32 s40, s44
	s_cselect_b64 s[80:81], -1, 0
	s_cmp_ge_u32 s40, s44
	s_cbranch_scc1 .LBB0_578
	s_mov_b64 s[40:41], -1
	s_and_b64 vcc, exec, s[56:57]
	s_cbranch_vccz .LBB0_573
	s_waitcnt vmcnt(1)
	v_lshlrev_b32_e32 v94, 16, v4
	v_and_b32_e32 v95, 0xffff0000, v4
	v_lshlrev_b32_e32 v96, 16, v0
	v_and_b32_e32 v97, 0xffff0000, v0
	v_lshlrev_b32_e32 v98, 16, v5
	v_and_b32_e32 v99, 0xffff0000, v5
	v_lshlrev_b32_e32 v100, 16, v1
	v_and_b32_e32 v101, 0xffff0000, v1
	v_lshlrev_b32_e32 v102, 16, v6
	v_and_b32_e32 v103, 0xffff0000, v6
	v_lshlrev_b32_e32 v104, 16, v2
	v_and_b32_e32 v105, 0xffff0000, v2
	v_lshlrev_b32_e32 v190, 16, v7
	v_and_b32_e32 v191, 0xffff0000, v7
	v_lshlrev_b32_e32 v192, 16, v3
	v_and_b32_e32 v193, 0xffff0000, v3
	s_waitcnt vmcnt(0)
	v_lshlrev_b32_e32 v194, 16, v8
	v_and_b32_e32 v195, 0xffff0000, v8
	v_lshlrev_b32_e32 v196, 16, v28
	v_and_b32_e32 v197, 0xffff0000, v28
	v_lshlrev_b32_e32 v198, 16, v9
	v_and_b32_e32 v199, 0xffff0000, v9
	v_lshlrev_b32_e32 v200, 16, v29
	v_and_b32_e32 v201, 0xffff0000, v29
	v_lshlrev_b32_e32 v202, 16, v10
	v_and_b32_e32 v203, 0xffff0000, v10
	v_lshlrev_b32_e32 v204, 16, v30
	v_and_b32_e32 v205, 0xffff0000, v30
	v_lshlrev_b32_e32 v206, 16, v11
	v_and_b32_e32 v207, 0xffff0000, v11
	v_lshlrev_b32_e32 v208, 16, v31
	v_and_b32_e32 v209, 0xffff0000, v31
	v_lshlrev_b32_e32 v56, 16, v12
	v_and_b32_e32 v57, 0xffff0000, v12
	v_lshlrev_b32_e32 v58, 16, v13
	v_and_b32_e32 v59, 0xffff0000, v13
	v_lshlrev_b32_e32 v60, 16, v14
	v_and_b32_e32 v61, 0xffff0000, v14
	v_lshlrev_b32_e32 v62, 16, v15
	v_and_b32_e32 v63, 0xffff0000, v15
	v_lshlrev_b32_e32 v64, 16, v16
	v_and_b32_e32 v65, 0xffff0000, v16
	v_lshlrev_b32_e32 v66, 16, v17
	v_and_b32_e32 v67, 0xffff0000, v17
	v_lshlrev_b32_e32 v68, 16, v18
	v_and_b32_e32 v69, 0xffff0000, v18
	v_lshlrev_b32_e32 v70, 16, v19
	v_and_b32_e32 v71, 0xffff0000, v19
	v_pk_add_f32 v[106:107], v[94:95], v[96:97]
	v_pk_add_f32 v[108:109], v[98:99], v[100:101]
	s_and_b64 vcc, exec, s[58:59]
	v_pk_add_f32 v[102:103], v[102:103], v[104:105]
	v_pk_add_f32 v[104:105], v[190:191], v[192:193]
	v_pk_add_f32 v[98:99], v[194:195], v[196:197]
	v_pk_add_f32 v[100:101], v[198:199], v[200:201]
	v_pk_add_f32 v[94:95], v[202:203], v[204:205]
	v_pk_add_f32 v[96:97], v[206:207], v[208:209]
	s_cbranch_vccz .LBB0_570
	v_add_u32_e32 v228, v137, v255
	v_sub_u32_e32 v229, v137, v255
	v_add_u32_e32 v230, v138, v255
	v_sub_u32_e32 v231, v138, v255
	v_add_u32_e32 v232, v139, v255
	v_sub_u32_e32 v233, v139, v255
	v_add_u32_e32 v234, v140, v255
	v_sub_u32_e32 v235, v140, v255
	v_add_u32_e32 v236, v141, v255
	v_sub_u32_e32 v237, v141, v255
	v_add_u32_e32 v238, v142, v255
	v_sub_u32_e32 v239, v142, v255
	v_add_u32_e32 v240, v177, v255
	v_sub_u32_e32 v241, v177, v255
	ds_read_b128 v[190:193], v228
	ds_read_b128 v[194:197], v228 offset:16
	ds_read_b128 v[198:201], v229 offset:32
	ds_read_b128 v[202:205], v229 offset:48
	ds_read_b128 v[206:209], v230
	ds_read_b128 v[210:213], v230 offset:16
	ds_read_b128 v[214:217], v231 offset:32
	ds_read_b128 v[218:221], v231 offset:48
	s_mov_b32 s40, 0xf800000
	s_waitcnt lgkmcnt(3)
	v_pk_mul_f32 v[206:207], v[106:107], v[206:207]
	s_nop 0
	v_pk_fma_f32 v[190:191], v[190:191], v[56:57], v[206:207]
	v_pk_mul_f32 v[206:207], v[108:109], v[208:209]
	s_nop 0
	v_pk_fma_f32 v[192:193], v[192:193], v[58:59], v[206:207]
	s_waitcnt lgkmcnt(2)
	v_pk_mul_f32 v[206:207], v[102:103], v[210:211]
	ds_write_b128 v232, v[190:193]
	v_pk_fma_f32 v[194:195], v[194:195], v[60:61], v[206:207]
	v_pk_mul_f32 v[206:207], v[104:105], v[212:213]
	s_nop 0
	v_pk_fma_f32 v[196:197], v[196:197], v[62:63], v[206:207]
	s_waitcnt lgkmcnt(2)
	v_pk_mul_f32 v[206:207], v[98:99], v[214:215]
	ds_write_b128 v232, v[194:197] offset:16
	v_pk_fma_f32 v[198:199], v[198:199], v[64:65], v[206:207]
	v_pk_mul_f32 v[206:207], v[100:101], v[216:217]
	s_nop 0
	v_pk_fma_f32 v[200:201], v[200:201], v[66:67], v[206:207]
	ds_read_b128 v[206:209], v231 offset:1312
	ds_write_b128 v233, v[198:201] offset:32
	s_waitcnt lgkmcnt(1)
	v_pk_mul_f32 v[212:213], v[200:201], v[208:209]
	v_pk_mul_f32 v[208:209], v[94:95], v[218:219]
	v_pk_mul_f32 v[198:199], v[198:199], v[206:207]
	v_pk_fma_f32 v[202:203], v[202:203], v[68:69], v[208:209]
	ds_read_b128 v[208:211], v231 offset:1328
	v_pk_mul_f32 v[200:201], v[198:199], v[198:199]
	v_pk_mul_f32 v[214:215], v[212:213], v[212:213]
	v_lshlrev_b32_e32 v206, 16, v36
	v_and_b32_e32 v207, 0xffff0000, v36
	s_waitcnt lgkmcnt(0)
	v_pk_mul_f32 v[216:217], v[202:203], v[208:209]
	v_pk_mul_f32 v[208:209], v[96:97], v[220:221]
	v_pk_mul_f32 v[218:219], v[216:217], v[216:217]
	v_pk_fma_f32 v[204:205], v[204:205], v[70:71], v[208:209]
	s_nop 0
	v_pk_mul_f32 v[220:221], v[204:205], v[210:211]
	ds_read_b128 v[208:211], v230 offset:1280
	v_pk_mul_f32 v[222:223], v[220:221], v[220:221]
	s_waitcnt lgkmcnt(0)
	v_pk_mul_f32 v[208:209], v[190:191], v[208:209]
	v_pk_mul_f32 v[210:211], v[192:193], v[210:211]
	ds_read_b128 v[190:193], v230 offset:1296
	v_pk_mul_f32 v[224:225], v[208:209], v[208:209]
	v_pk_mul_f32 v[226:227], v[210:211], v[210:211]
	v_add_f32_e32 v78, v224, v225
	v_add_f32_e32 v78, v78, v226
	s_waitcnt lgkmcnt(0)
; __device__ __forceinline__ float quad_sum(float x) { x += dpp_f<0xB1>(x); x += dpp_f<0x4E>(x); return x; }
; __device__ __forceinline__ void scan_phase(PREF p, char* smem, const int wid_u) {
;     ...
;           float kk[16], ss = 0.f;
; #pragma unroll
;           for (int q = 0; q < 16; ++q) { kk[q] = v16[q] * cst[5 * 64 + cq * 16 + q]; ss += kk[q] * kk[q]; }
;           ss = quad_sum(ss);
;           const float inv = 1.f / fmaxf(sqrtf(ss), 1e-12f);
; #pragma unroll
;           for (int q = 0; q < 4; ++q) {
;             *(f32x4*)(stepbuf + 1 * SV + j * 64 + cq * 16 + q * 4) = (f32x4){v16[q * 4], v16[q * 4 + 1], v16[q * 4 + 2], v16[q * 4 + 3]};
;             *(f32x4*)(stepbuf + 3 * SV + j * 64 + cq * 16 + q * 4) = (f32x4){-kk[q * 4] * inv, -kk[q * 4 + 1] * inv, -kk[q * 4 + 2] * inv, -kk[q * 4 + 3] * inv};
;           }
;           shift16(rb, cst + 4 * 64 + cq * 16, cst + 8 * 64 + cq * 16, v16);
; #pragma unroll
;           for (int q = 0; q < 4; ++q) *(f32x4*)(stepbuf + 5 * SV + j * 64 + cq * 16 + q * 4) = (f32x4){v16[q * 4], v16[q * 4 + 1], v16[q * 4 + 2], v16[q * 4 + 3]};
	v_pk_mul_f32 v[194:195], v[194:195], v[190:191]
	v_add_f32_e32 v78, v78, v227
	v_pk_mul_f32 v[190:191], v[194:195], v[194:195]
	v_pk_mul_f32 v[196:197], v[196:197], v[192:193]
	v_add_f32_e32 v78, v78, v190
	v_pk_mul_f32 v[192:193], v[196:197], v[196:197]
	v_add_f32_e32 v78, v78, v191
	v_add_f32_e32 v78, v78, v192
	v_add_f32_e32 v78, v78, v193
	v_add_f32_e32 v78, v78, v200
	v_add_f32_e32 v78, v78, v201
	v_add_f32_e32 v78, v78, v214
	v_add_f32_e32 v78, v78, v215
	v_add_f32_e32 v78, v78, v218
	v_add_f32_e32 v78, v78, v219
	v_add_f32_e32 v78, v78, v222
	v_add_f32_e32 v78, v78, v223
	v_lshlrev_b32_e32 v222, 16, v24
	v_and_b32_e32 v223, 0xffff0000, v24
	v_add_f32_dpp v78, v78, v78 quad_perm:[1,0,3,2] row_mask:0xf bank_mask:0xf bound_ctrl:1
	s_nop 1
	v_add_f32_dpp v78, v78, v78 quad_perm:[2,3,0,1] row_mask:0xf bank_mask:0xf bound_ctrl:1
	v_cmp_gt_f32_e32 vcc, s40, v78
	v_mul_f32_e32 v189, 0x4f800000, v78
	s_nop 0
	v_cndmask_b32_e32 v78, v78, v189, vcc
	v_sqrt_f32_e32 v189, v78
	s_nop 0
	v_add_u32_e32 v190, -1, v189
	v_fma_f32 v191, -v190, v189, v78
	v_cmp_ge_f32_e64 s[40:41], 0, v191
	v_add_u32_e32 v191, 1, v189
	s_nop 0
	v_cndmask_b32_e64 v190, v189, v190, s[40:41]
	v_fma_f32 v189, -v191, v189, v78
	v_cmp_lt_f32_e64 s[40:41], 0, v189
	s_nop 1
	v_cndmask_b32_e64 v189, v190, v191, s[40:41]
	v_mul_f32_e32 v190, 0x37800000, v189
	v_cndmask_b32_e32 v189, v189, v190, vcc
	v_cmp_class_f32_e32 vcc, v78, v176
	s_nop 1
	v_cndmask_b32_e32 v78, v189, v78, vcc
	v_max_f32_e32 v78, 0x2b8cbccc, v78
	v_div_scale_f32 v189, s[40:41], v78, v78, 1.0
	v_rcp_f32_e32 v190, v189
	s_mov_b64 s[40:41], 0
	v_fma_f32 v191, -v189, v190, 1.0
	v_fmac_f32_e32 v190, v191, v190
	v_div_scale_f32 v191, vcc, 1.0, v78, 1.0
	v_mul_f32_e32 v192, v191, v190
	v_fma_f32 v193, -v189, v192, v191
	v_fmac_f32_e32 v192, v193, v190
	v_fma_f32 v189, -v189, v192, v191
	v_div_fmas_f32 v189, v189, v190, v192
	v_div_fixup_f32 v78, v189, v78, 1.0
	v_pk_mul_f32 v[192:193], v[78:79], v[210:211] op_sel_hi:[0,1] neg_lo:[0,1] neg_hi:[0,1]
	v_pk_mul_f32 v[190:191], v[78:79], v[208:209] op_sel_hi:[0,1] neg_lo:[0,1] neg_hi:[0,1]
	ds_write_b128 v234, v[190:193]
	v_pk_mul_f32 v[192:193], v[78:79], v[196:197] op_sel_hi:[0,1] neg_lo:[0,1] neg_hi:[0,1]
	v_pk_mul_f32 v[190:191], v[78:79], v[194:195] op_sel_hi:[0,1] neg_lo:[0,1] neg_hi:[0,1]
	ds_write_b128 v234, v[190:193] offset:16
	v_pk_mul_f32 v[192:193], v[78:79], v[212:213] op_sel_hi:[0,1] neg_lo:[0,1] neg_hi:[0,1]
	v_pk_mul_f32 v[190:191], v[78:79], v[198:199] op_sel_hi:[0,1] neg_lo:[0,1] neg_hi:[0,1]
	ds_write_b128 v235, v[190:193] offset:32
	ds_write_b128 v233, v[202:205] offset:48
	v_pk_mul_f32 v[192:193], v[78:79], v[220:221] op_sel_hi:[0,1] neg_lo:[0,1] neg_hi:[0,1]
	v_pk_mul_f32 v[190:191], v[78:79], v[216:217] op_sel_hi:[0,1] neg_lo:[0,1] neg_hi:[0,1]
	ds_write_b128 v235, v[190:193] offset:48
	v_lshlrev_b32_e32 v208, 16, v32
	v_and_b32_e32 v209, 0xffff0000, v32
	ds_read_b128 v[190:193], v236
	ds_read_b128 v[194:197], v236 offset:16
	ds_read_b128 v[198:201], v237 offset:32
	ds_read_b128 v[202:205], v237 offset:48
	v_pk_add_f32 v[224:225], v[206:207], v[208:209]
	ds_read_b128 v[206:209], v238
	ds_read_b128 v[210:213], v238 offset:16
	ds_read_b128 v[214:217], v239 offset:32
	ds_read_b128 v[218:221], v239 offset:48
	s_waitcnt lgkmcnt(3)
	v_pk_mul_f32 v[206:207], v[224:225], v[206:207]
	s_nop 0
	v_pk_fma_f32 v[190:191], v[190:191], v[222:223], v[206:207]
	v_lshlrev_b32_e32 v222, 16, v37
	v_and_b32_e32 v223, 0xffff0000, v37
	v_lshlrev_b32_e32 v224, 16, v33
	v_and_b32_e32 v225, 0xffff0000, v33
	v_pk_add_f32 v[222:223], v[222:223], v[224:225]
	v_lshlrev_b32_e32 v206, 16, v25
	v_and_b32_e32 v207, 0xffff0000, v25
	v_pk_mul_f32 v[208:209], v[222:223], v[208:209]
	v_lshlrev_b32_e32 v222, 16, v34
	v_pk_fma_f32 v[192:193], v[192:193], v[206:207], v[208:209]
	v_lshlrev_b32_e32 v208, 16, v38
	v_and_b32_e32 v209, 0xffff0000, v38
	v_and_b32_e32 v223, 0xffff0000, v34
	v_pk_add_f32 v[208:209], v[208:209], v[222:223]
	v_lshlrev_b32_e32 v206, 16, v26
	v_and_b32_e32 v207, 0xffff0000, v26
	s_waitcnt lgkmcnt(2)
	v_pk_mul_f32 v[208:209], v[208:209], v[210:211]
	v_lshlrev_b32_e32 v210, 16, v35
	v_pk_fma_f32 v[194:195], v[194:195], v[206:207], v[208:209]
	v_lshlrev_b32_e32 v208, 16, v39
	v_and_b32_e32 v209, 0xffff0000, v39
	v_and_b32_e32 v211, 0xffff0000, v35
	v_pk_add_f32 v[208:209], v[208:209], v[210:211]
	v_lshlrev_b32_e32 v206, 16, v27
	v_and_b32_e32 v207, 0xffff0000, v27
	v_pk_mul_f32 v[208:209], v[208:209], v[212:213]
	v_lshlrev_b32_e32 v210, 16, v44
	v_pk_fma_f32 v[196:197], v[196:197], v[206:207], v[208:209]
	v_lshlrev_b32_e32 v208, 16, v40
	v_and_b32_e32 v209, 0xffff0000, v40
	v_and_b32_e32 v211, 0xffff0000, v44
	v_pk_add_f32 v[208:209], v[208:209], v[210:211]
	v_lshlrev_b32_e32 v206, 16, v20
	v_and_b32_e32 v207, 0xffff0000, v20
	s_waitcnt lgkmcnt(1)
	v_pk_mul_f32 v[208:209], v[208:209], v[214:215]
	v_lshlrev_b32_e32 v210, 16, v45
	v_pk_fma_f32 v[198:199], v[198:199], v[206:207], v[208:209]
	v_lshlrev_b32_e32 v208, 16, v41
	v_and_b32_e32 v209, 0xffff0000, v41
	v_and_b32_e32 v211, 0xffff0000, v45
	v_pk_add_f32 v[208:209], v[208:209], v[210:211]
	v_lshlrev_b32_e32 v206, 16, v21
	v_and_b32_e32 v207, 0xffff0000, v21
	v_pk_mul_f32 v[208:209], v[208:209], v[216:217]
	v_lshlrev_b32_e32 v210, 16, v46
	v_pk_fma_f32 v[200:201], v[200:201], v[206:207], v[208:209]
	v_lshlrev_b32_e32 v208, 16, v42
	v_and_b32_e32 v209, 0xffff0000, v42
	v_and_b32_e32 v211, 0xffff0000, v46
	v_pk_add_f32 v[208:209], v[208:209], v[210:211]
	v_lshlrev_b32_e32 v206, 16, v22
	v_and_b32_e32 v207, 0xffff0000, v22
	s_waitcnt lgkmcnt(0)
	v_pk_mul_f32 v[208:209], v[208:209], v[218:219]
	v_lshlrev_b32_e32 v210, 16, v47
	v_pk_fma_f32 v[202:203], v[202:203], v[206:207], v[208:209]
	v_lshlrev_b32_e32 v208, 16, v43
	v_and_b32_e32 v209, 0xffff0000, v43
	v_and_b32_e32 v211, 0xffff0000, v47
	v_pk_add_f32 v[208:209], v[208:209], v[210:211]
	v_lshlrev_b32_e32 v206, 16, v23
	v_and_b32_e32 v207, 0xffff0000, v23
	v_pk_mul_f32 v[208:209], v[208:209], v[220:221]
	s_nop 0
	v_pk_fma_f32 v[204:205], v[204:205], v[206:207], v[208:209]
	ds_write_b128 v240, v[190:193]
	ds_write_b128 v240, v[194:197] offset:16
	ds_write_b128 v241, v[198:201] offset:32
	ds_write_b128 v241, v[202:205] offset:48
; __device__ __forceinline__ void scan_phase(PREF p, char* smem, const int wid_u) {
;     ...
;         } else if (role == 2) {
;           shift16(ra, cst + 3 * 64 + cq * 16, cst + 1 * 64 + cq * 16, v16);
; #pragma unroll
;           for (int q = 0; q < 4; ++q) *(f32x4*)(stepbuf + 2 * SV + j * 64 + cq * 16 + q * 4) = (f32x4){v16[q * 4], v16[q * 4 + 1], v16[q * 4 + 2], v16[q * 4 + 3]};
.LBB0_570:
	s_andn2_b64 vcc, exec, s[40:41]
	s_cbranch_vccnz .LBB0_572
	v_add_u32_e32 v242, v143, v255
	v_sub_u32_e32 v243, v143, v255
	v_add_u32_e32 v244, v144, v255
	v_sub_u32_e32 v245, v144, v255
	v_add_u32_e32 v246, v178, v255
	v_sub_u32_e32 v247, v178, v255
	ds_read_b128 v[190:193], v242
	ds_read_b128 v[194:197], v242 offset:16
	ds_read_b128 v[198:201], v244
	ds_read_b128 v[202:205], v243 offset:32
	ds_read_b128 v[206:209], v243 offset:48
	ds_read_b128 v[210:213], v244 offset:16
	ds_read_b128 v[214:217], v245 offset:32
	ds_read_b128 v[218:221], v245 offset:48
	s_waitcnt lgkmcnt(5)
	v_pk_mul_f32 v[106:107], v[106:107], v[198:199]
	v_pk_mul_f32 v[108:109], v[108:109], v[200:201]
	v_pk_fma_f32 v[56:57], v[190:191], v[56:57], v[106:107]
	v_pk_fma_f32 v[58:59], v[192:193], v[58:59], v[108:109]
	ds_write_b128 v246, v[56:59]
	s_waitcnt lgkmcnt(3)
	v_pk_mul_f32 v[56:57], v[102:103], v[210:211]
	v_pk_mul_f32 v[58:59], v[104:105], v[212:213]
	v_pk_fma_f32 v[56:57], v[194:195], v[60:61], v[56:57]
	v_pk_fma_f32 v[58:59], v[196:197], v[62:63], v[58:59]
	ds_write_b128 v246, v[56:59] offset:16
	s_waitcnt lgkmcnt(3)
	v_pk_mul_f32 v[56:57], v[98:99], v[214:215]
	v_pk_mul_f32 v[58:59], v[100:101], v[216:217]
	v_pk_fma_f32 v[56:57], v[202:203], v[64:65], v[56:57]
	v_pk_fma_f32 v[58:59], v[204:205], v[66:67], v[58:59]
	ds_write_b128 v247, v[56:59] offset:32
	s_waitcnt lgkmcnt(3)
	v_pk_mul_f32 v[56:57], v[94:95], v[218:219]
	v_pk_mul_f32 v[58:59], v[96:97], v[220:221]
	v_pk_fma_f32 v[56:57], v[206:207], v[68:69], v[56:57]
	v_pk_fma_f32 v[58:59], v[208:209], v[70:71], v[58:59]
	ds_write_b128 v247, v[56:59] offset:48

; __device__ __forceinline__ void load_raw16(Raw16& r, const bf16_t* __restrict__ z, int row, int t, int T, int col) {
;   const bf16_t* pz = z + (unsigned)(row * ZLD + col);
;   r.c0 = *(const uint4*)pz; r.c1 = *(const uint4*)(pz + 8);
;   r.p0 = make_uint4(0, 0, 0, 0); r.p1 = r.p0; r.n0 = r.p0; r.n1 = r.p0;
;   if (t > 0) { r.p0 = *(const uint4*)(pz - ZLD); r.p1 = *(const uint4*)(pz - ZLD + 8); }
;   if (t < T - 1) { r.n0 = *(const uint4*)(pz + ZLD); r.n1 = *(const uint4*)(pz + ZLD + 8); }
; __device__ __forceinline__ void scan_phase(PREF p, char* smem, const int wid_u) {
;     ...
;       if (c + 2 < nch) {
;         const int is2 = (c + 2) * 32 + th * 16 + tl;
;         const int t2 = d ? T - 1 - is2 : is2;
;         const int row2 = r0seq + t2;
;         if (role >= 2) load_raw16(ra, z, row2, t2, T, colA);
;         if (role == 3) load_raw16(rb, z, row2, t2, T, colB);
.LBB0_592:
	v_mad_u64_u32 v[0:1], s[82:83], v59, s88, v[74:75]
	v_mov_b32_e32 v1, v79
	v_lshl_add_u64 v[56:57], v[0:1], 1, s[50:51]
	v_xor_b32_e32 v250, 16, v56
	v_mov_b32_e32 v251, v57
	global_load_dwordx4 v[12:15], v[56:57], off
	global_load_dwordx4 v[16:19], v[250:251], off
	v_mov_b32_e32 v2, v79
	v_mov_b32_e32 v3, v79
	v_mov_b32_e32 v0, 0
	v_mov_b64_e32 v[10:11], v[2:3]
	v_mov_b64_e32 v[6:7], v[2:3]
	v_mov_b64_e32 v[8:9], v[0:1]
	v_mov_b64_e32 v[4:5], v[0:1]
	s_and_saveexec_b64 s[82:83], s[40:41]
	s_cbranch_execz .LBB0_594
	v_add_co_u32_e32 v4, vcc, 0xfffff000, v56
	v_lshl_add_u64 v[8:9], v[56:57], 0, s[76:77]
	s_nop 0
	v_addc_co_u32_e32 v5, vcc, -1, v57, vcc
	global_load_dwordx4 v[4:7], v[4:5], off offset:-1024
	s_nop 0
	v_xor_b32_e32 v8, 16, v8
	global_load_dwordx4 v[8:11], v[8:9], off
.LBB0_594:
	s_or_b64 exec, exec, s[82:83]
	v_mov_b64_e32 v[30:31], v[2:3]
	v_cmp_gt_i32_e32 vcc, s45, v58
	v_mov_b64_e32 v[28:29], v[0:1]
	s_and_saveexec_b64 s[40:41], vcc
	s_cbranch_execz .LBB0_596
	v_add_co_u32_e32 v0, vcc, 0x1000, v56
	v_lshl_add_u64 v[28:29], v[56:57], 0, s[78:79]
	s_nop 0
	v_addc_co_u32_e32 v1, vcc, 0, v57, vcc
	global_load_dwordx4 v[0:3], v[0:1], off offset:1024
	s_nop 0
	v_xor_b32_e32 v28, 16, v28
	global_load_dwordx4 v[28:31], v[28:29], off

; __device__ __forceinline__ void load_raw16(Raw16& r, const bf16_t* __restrict__ z, int row, int t, int T, int col) {
;   const bf16_t* pz = z + (unsigned)(row * ZLD + col);
;   r.c0 = *(const uint4*)pz; r.c1 = *(const uint4*)(pz + 8);
;   r.p0 = make_uint4(0, 0, 0, 0); r.p1 = r.p0; r.n0 = r.p0; r.n1 = r.p0;
;   if (t > 0) { r.p0 = *(const uint4*)(pz - ZLD); r.p1 = *(const uint4*)(pz - ZLD + 8); }
;   if (t < T - 1) { r.n0 = *(const uint4*)(pz + ZLD); r.n1 = *(const uint4*)(pz + ZLD + 8); }
; __device__ __forceinline__ void scan_phase(PREF p, char* smem, const int wid_u) {
;     ...
;         if (role == 3) load_raw16(rb, z, row2, t2, T, colB);
.LBB0_597:
	v_mad_u64_u32 v[20:21], s[40:41], v59, s88, v[76:77]
	v_mov_b32_e32 v21, v79
	v_lshl_add_u64 v[56:57], v[20:21], 1, s[50:51]
	v_xor_b32_e32 v250, 16, v56
	v_mov_b32_e32 v251, v57
	global_load_dwordx4 v[24:27], v[56:57], off
	global_load_dwordx4 v[20:23], v[250:251], off
	v_mov_b32_e32 v34, v79
	v_mov_b32_e32 v35, v79
	v_mov_b32_e32 v32, 0
	v_mov_b32_e32 v33, v79
	v_mov_b64_e32 v[42:43], v[34:35]
	v_mov_b64_e32 v[38:39], v[34:35]
	v_cmp_lt_i32_e32 vcc, 0, v58
	v_mov_b64_e32 v[40:41], v[32:33]
	v_mov_b64_e32 v[36:37], v[32:33]
	s_and_saveexec_b64 s[40:41], vcc
	s_cbranch_execz .LBB0_599
	v_add_co_u32_e32 v36, vcc, 0xfffff000, v56
	v_lshl_add_u64 v[40:41], v[56:57], 0, s[76:77]
	s_nop 0
	v_addc_co_u32_e32 v37, vcc, -1, v57, vcc
	global_load_dwordx4 v[36:39], v[36:37], off offset:-1024
	s_nop 0
	v_xor_b32_e32 v40, 16, v40
	global_load_dwordx4 v[40:43], v[40:41], off
.LBB0_599:
	s_or_b64 exec, exec, s[40:41]
	v_mov_b64_e32 v[46:47], v[34:35]
	v_cmp_gt_i32_e32 vcc, s45, v58
	v_mov_b64_e32 v[44:45], v[32:33]
	s_and_saveexec_b64 s[40:41], vcc
	s_cbranch_execz .LBB0_601
	v_add_co_u32_e32 v32, vcc, 0x1000, v56
	v_lshl_add_u64 v[44:45], v[56:57], 0, s[78:79]
	s_nop 0
	v_addc_co_u32_e32 v33, vcc, 0, v57, vcc
	global_load_dwordx4 v[32:35], v[32:33], off offset:1024
	s_nop 0
	v_xor_b32_e32 v44, 16, v44
	global_load_dwordx4 v[44:47], v[44:45], off
